# t1 + GEMM tile-head accumulator zeroing with 64 v_mov_b64 instead of 128 v_mov_b32 (8 sites)
# speedup vs baseline: 1.0013x; 1.0013x over previous
.LBB0_273:
	s_ashr_i32 s15, s14, 31
	s_lshl_b64 s[16:17], s[14:15], 20
	s_add_u32 s16, s26, s16
	s_addc_u32 s17, s27, s17
	s_and_b64 s[18:19], s[4:5], exec
	s_cselect_b32 s15, s17, s21
	s_cselect_b32 s41, s16, s20
	s_ashr_i32 s13, s12, 31
	s_lshl_b64 s[18:19], s[12:13], 20
	s_add_u32 s18, s28, s18
	s_addc_u32 s19, s29, s19
	s_and_b64 s[24:25], s[4:5], exec
	s_cselect_b32 s13, s19, s23
	s_cselect_b32 s42, s18, s22
	s_add_u32 s20, s20, 0x80080
	s_addc_u32 s21, s21, 0
	s_add_u32 s43, s22, 0x100
	v_mov_b32_e32 v0, 0
	s_addc_u32 s44, s23, 0
	s_mov_b32 s45, -2
	v_mov_b64_e32 v[0:1], 0
	v_mov_b64_e32 v[2:3], 0
	v_mov_b64_e32 v[4:5], 0
	v_mov_b64_e32 v[6:7], 0
	v_mov_b64_e32 v[8:9], 0
	v_mov_b64_e32 v[10:11], 0
	v_mov_b64_e32 v[12:13], 0
	v_mov_b64_e32 v[14:15], 0
	v_mov_b64_e32 v[16:17], 0
	v_mov_b64_e32 v[18:19], 0
	v_mov_b64_e32 v[20:21], 0
	v_mov_b64_e32 v[22:23], 0
	v_mov_b64_e32 v[24:25], 0
	v_mov_b64_e32 v[26:27], 0
	v_mov_b64_e32 v[28:29], 0
	v_mov_b64_e32 v[30:31], 0
	v_mov_b64_e32 v[32:33], 0
	v_mov_b64_e32 v[34:35], 0
	v_mov_b64_e32 v[36:37], 0
	v_mov_b64_e32 v[38:39], 0
	v_mov_b64_e32 v[40:41], 0
	v_mov_b64_e32 v[42:43], 0
	v_mov_b64_e32 v[44:45], 0
	v_mov_b64_e32 v[46:47], 0
	v_mov_b64_e32 v[48:49], 0
	v_mov_b64_e32 v[50:51], 0
	v_mov_b64_e32 v[52:53], 0
	v_mov_b64_e32 v[54:55], 0
	v_mov_b64_e32 v[56:57], 0
	v_mov_b64_e32 v[58:59], 0
	v_mov_b64_e32 v[60:61], 0
	v_mov_b64_e32 v[62:63], 0
	v_mov_b64_e32 v[64:65], 0
	v_mov_b64_e32 v[66:67], 0
	v_mov_b64_e32 v[68:69], 0
	v_mov_b64_e32 v[70:71], 0
	v_mov_b64_e32 v[72:73], 0
	v_mov_b64_e32 v[74:75], 0
	v_mov_b64_e32 v[76:77], 0
	v_mov_b64_e32 v[78:79], 0
	v_mov_b64_e32 v[80:81], 0
	v_mov_b64_e32 v[82:83], 0
	v_mov_b64_e32 v[84:85], 0
	v_mov_b64_e32 v[86:87], 0
	v_mov_b64_e32 v[88:89], 0
	v_mov_b64_e32 v[90:91], 0
	v_mov_b64_e32 v[92:93], 0
	v_mov_b64_e32 v[94:95], 0
	v_mov_b64_e32 v[96:97], 0
	v_mov_b64_e32 v[98:99], 0
	v_mov_b64_e32 v[100:101], 0
	v_mov_b64_e32 v[102:103], 0
	v_mov_b64_e32 v[104:105], 0
	v_mov_b64_e32 v[106:107], 0
	v_mov_b64_e32 v[108:109], 0
	v_mov_b64_e32 v[110:111], 0
	v_mov_b64_e32 v[112:113], 0
	v_mov_b64_e32 v[114:115], 0
	v_mov_b64_e32 v[116:117], 0
	v_mov_b64_e32 v[118:119], 0
	v_mov_b64_e32 v[120:121], 0
	v_mov_b64_e32 v[122:123], 0
	v_mov_b64_e32 v[124:125], 0
	v_mov_b64_e32 v[126:127], 0

.LBB0_393:
	s_ashr_i32 s13, s12, 31
	s_lshl_b64 s[16:17], s[12:13], 20
	s_add_u32 s16, s26, s16
	s_addc_u32 s17, s27, s17
	s_and_b64 s[18:19], s[4:5], exec
	s_cselect_b32 s13, s17, s21
	s_cselect_b32 s41, s16, s20
	s_ashr_i32 s15, s14, 31
	s_lshl_b64 s[18:19], s[14:15], 20
	s_add_u32 s18, s28, s18
	s_addc_u32 s19, s29, s19
	s_and_b64 s[24:25], s[4:5], exec
	s_cselect_b32 s15, s19, s23
	s_cselect_b32 s42, s18, s22
	s_add_u32 s20, s20, 0x80080
	s_addc_u32 s21, s21, 0
	s_add_u32 s43, s22, 0x100
	v_mov_b32_e32 v0, 0
	s_addc_u32 s44, s23, 0
	s_mov_b32 s45, -2
	v_mov_b64_e32 v[0:1], 0
	v_mov_b64_e32 v[2:3], 0
	v_mov_b64_e32 v[4:5], 0
	v_mov_b64_e32 v[6:7], 0
	v_mov_b64_e32 v[8:9], 0
	v_mov_b64_e32 v[10:11], 0
	v_mov_b64_e32 v[12:13], 0
	v_mov_b64_e32 v[14:15], 0
	v_mov_b64_e32 v[16:17], 0
	v_mov_b64_e32 v[18:19], 0
	v_mov_b64_e32 v[20:21], 0
	v_mov_b64_e32 v[22:23], 0
	v_mov_b64_e32 v[24:25], 0
	v_mov_b64_e32 v[26:27], 0
	v_mov_b64_e32 v[28:29], 0
	v_mov_b64_e32 v[30:31], 0
	v_mov_b64_e32 v[32:33], 0
	v_mov_b64_e32 v[34:35], 0
	v_mov_b64_e32 v[36:37], 0
	v_mov_b64_e32 v[38:39], 0
	v_mov_b64_e32 v[40:41], 0
	v_mov_b64_e32 v[42:43], 0
	v_mov_b64_e32 v[44:45], 0
	v_mov_b64_e32 v[46:47], 0
	v_mov_b64_e32 v[48:49], 0
	v_mov_b64_e32 v[50:51], 0
	v_mov_b64_e32 v[52:53], 0
	v_mov_b64_e32 v[54:55], 0
	v_mov_b64_e32 v[56:57], 0
	v_mov_b64_e32 v[58:59], 0
	v_mov_b64_e32 v[60:61], 0
	v_mov_b64_e32 v[62:63], 0
	v_mov_b64_e32 v[64:65], 0
	v_mov_b64_e32 v[66:67], 0
	v_mov_b64_e32 v[68:69], 0
	v_mov_b64_e32 v[70:71], 0
	v_mov_b64_e32 v[72:73], 0
	v_mov_b64_e32 v[74:75], 0
	v_mov_b64_e32 v[76:77], 0
	v_mov_b64_e32 v[78:79], 0
	v_mov_b64_e32 v[80:81], 0
	v_mov_b64_e32 v[82:83], 0
	v_mov_b64_e32 v[84:85], 0
	v_mov_b64_e32 v[86:87], 0
	v_mov_b64_e32 v[88:89], 0
	v_mov_b64_e32 v[90:91], 0
	v_mov_b64_e32 v[92:93], 0
	v_mov_b64_e32 v[94:95], 0
	v_mov_b64_e32 v[96:97], 0
	v_mov_b64_e32 v[98:99], 0
	v_mov_b64_e32 v[100:101], 0
	v_mov_b64_e32 v[102:103], 0
	v_mov_b64_e32 v[104:105], 0
	v_mov_b64_e32 v[106:107], 0
	v_mov_b64_e32 v[108:109], 0
	v_mov_b64_e32 v[110:111], 0
	v_mov_b64_e32 v[112:113], 0
	v_mov_b64_e32 v[114:115], 0
	v_mov_b64_e32 v[116:117], 0
	v_mov_b64_e32 v[118:119], 0
	v_mov_b64_e32 v[120:121], 0
	v_mov_b64_e32 v[122:123], 0
	v_mov_b64_e32 v[124:125], 0
	v_mov_b64_e32 v[126:127], 0

.LBB0_409:
	s_ashr_i32 s15, s14, 31
	s_lshl_b64 s[6:7], s[14:15], 18
	s_add_u32 s15, s26, s6
	s_addc_u32 s17, s27, s7
	s_ashr_i32 s19, s18, 31
	s_lshl_b64 s[6:7], s[18:19], 9
	s_add_u32 s20, s15, s6
	s_addc_u32 s21, s17, s7
	s_and_b64 s[22:23], s[4:5], exec
	s_cselect_b32 s15, s21, s25
	s_cselect_b32 s19, s20, s24
	s_ashr_i32 s17, s16, 31
	s_lshl_b64 s[22:23], s[16:17], 18
	s_add_u32 s17, s28, s22
	s_addc_u32 s23, s29, s23
	s_add_u32 s22, s17, s6
	s_addc_u32 s23, s23, s7
	s_and_b64 s[6:7], s[4:5], exec
	s_cselect_b32 s17, s23, s9
	s_cselect_b32 s44, s22, s8
	s_add_i32 s45, s43, -2
	s_add_u32 s6, s24, 0x20080
	s_addc_u32 s7, s25, 0
	s_add_u32 s46, s8, 0x100
	v_mov_b32_e32 v0, 0
	s_addc_u32 s47, s9, 0
	s_mov_b32 s8, 0
	v_mov_b64_e32 v[0:1], 0
	v_mov_b64_e32 v[2:3], 0
	v_mov_b64_e32 v[4:5], 0
	v_mov_b64_e32 v[6:7], 0
	v_mov_b64_e32 v[8:9], 0
	v_mov_b64_e32 v[10:11], 0
	v_mov_b64_e32 v[12:13], 0
	v_mov_b64_e32 v[14:15], 0
	v_mov_b64_e32 v[16:17], 0
	v_mov_b64_e32 v[18:19], 0
	v_mov_b64_e32 v[20:21], 0
	v_mov_b64_e32 v[22:23], 0
	v_mov_b64_e32 v[24:25], 0
	v_mov_b64_e32 v[26:27], 0
	v_mov_b64_e32 v[28:29], 0
	v_mov_b64_e32 v[30:31], 0
	v_mov_b64_e32 v[32:33], 0
	v_mov_b64_e32 v[34:35], 0
	v_mov_b64_e32 v[36:37], 0
	v_mov_b64_e32 v[38:39], 0
	v_mov_b64_e32 v[40:41], 0
	v_mov_b64_e32 v[42:43], 0
	v_mov_b64_e32 v[44:45], 0
	v_mov_b64_e32 v[46:47], 0
	v_mov_b64_e32 v[48:49], 0
	v_mov_b64_e32 v[50:51], 0
	v_mov_b64_e32 v[52:53], 0
	v_mov_b64_e32 v[54:55], 0
	v_mov_b64_e32 v[56:57], 0
	v_mov_b64_e32 v[58:59], 0
	v_mov_b64_e32 v[60:61], 0
	v_mov_b64_e32 v[62:63], 0
	v_mov_b64_e32 v[64:65], 0
	v_mov_b64_e32 v[66:67], 0
	v_mov_b64_e32 v[68:69], 0
	v_mov_b64_e32 v[70:71], 0
	v_mov_b64_e32 v[72:73], 0
	v_mov_b64_e32 v[74:75], 0
	v_mov_b64_e32 v[76:77], 0
	v_mov_b64_e32 v[78:79], 0
	v_mov_b64_e32 v[80:81], 0
	v_mov_b64_e32 v[82:83], 0
	v_mov_b64_e32 v[84:85], 0
	v_mov_b64_e32 v[86:87], 0
	v_mov_b64_e32 v[88:89], 0
	v_mov_b64_e32 v[90:91], 0
	v_mov_b64_e32 v[92:93], 0
	v_mov_b64_e32 v[94:95], 0
	v_mov_b64_e32 v[96:97], 0
	v_mov_b64_e32 v[98:99], 0
	v_mov_b64_e32 v[100:101], 0
	v_mov_b64_e32 v[102:103], 0
	v_mov_b64_e32 v[104:105], 0
	v_mov_b64_e32 v[106:107], 0
	v_mov_b64_e32 v[108:109], 0
	v_mov_b64_e32 v[110:111], 0
	v_mov_b64_e32 v[112:113], 0
	v_mov_b64_e32 v[114:115], 0
	v_mov_b64_e32 v[116:117], 0
	v_mov_b64_e32 v[118:119], 0
	v_mov_b64_e32 v[120:121], 0
	v_mov_b64_e32 v[122:123], 0
	v_mov_b64_e32 v[124:125], 0
	v_mov_b64_e32 v[126:127], 0

.LBB0_841:
	s_ashr_i32 s17, s16, 31
	s_lshl_b64 s[18:19], s[16:17], 20
	s_add_u32 s18, s33, s18
	s_addc_u32 s19, s34, s19
	s_and_b64 s[20:21], s[4:5], exec
	s_cselect_b32 s17, s19, s23
	s_cselect_b32 s43, s18, s22
	s_ashr_i32 s15, s14, 31
	s_lshl_b64 s[20:21], s[14:15], 20
	s_add_u32 s20, s35, s20
	s_addc_u32 s21, s36, s21
	s_and_b64 s[26:27], s[4:5], exec
	s_cselect_b32 s15, s21, s25
	s_cselect_b32 s44, s20, s24
	s_add_u32 s22, s22, 0x80080
	s_addc_u32 s23, s23, 0
	s_add_u32 s45, s24, 0x100
	v_mov_b32_e32 v0, 0
	s_addc_u32 s46, s25, 0
	s_mov_b32 s47, -2
	v_mov_b64_e32 v[0:1], 0
	v_mov_b64_e32 v[2:3], 0
	v_mov_b64_e32 v[4:5], 0
	v_mov_b64_e32 v[6:7], 0
	v_mov_b64_e32 v[8:9], 0
	v_mov_b64_e32 v[10:11], 0
	v_mov_b64_e32 v[12:13], 0
	v_mov_b64_e32 v[14:15], 0
	v_mov_b64_e32 v[16:17], 0
	v_mov_b64_e32 v[18:19], 0
	v_mov_b64_e32 v[20:21], 0
	v_mov_b64_e32 v[22:23], 0
	v_mov_b64_e32 v[24:25], 0
	v_mov_b64_e32 v[26:27], 0
	v_mov_b64_e32 v[28:29], 0
	v_mov_b64_e32 v[30:31], 0
	v_mov_b64_e32 v[32:33], 0
	v_mov_b64_e32 v[34:35], 0
	v_mov_b64_e32 v[36:37], 0
	v_mov_b64_e32 v[38:39], 0
	v_mov_b64_e32 v[40:41], 0
	v_mov_b64_e32 v[42:43], 0
	v_mov_b64_e32 v[44:45], 0
	v_mov_b64_e32 v[46:47], 0
	v_mov_b64_e32 v[48:49], 0
	v_mov_b64_e32 v[50:51], 0
	v_mov_b64_e32 v[52:53], 0
	v_mov_b64_e32 v[54:55], 0
	v_mov_b64_e32 v[56:57], 0
	v_mov_b64_e32 v[58:59], 0
	v_mov_b64_e32 v[60:61], 0
	v_mov_b64_e32 v[62:63], 0
	v_mov_b64_e32 v[64:65], 0
	v_mov_b64_e32 v[66:67], 0
	v_mov_b64_e32 v[68:69], 0
	v_mov_b64_e32 v[70:71], 0
	v_mov_b64_e32 v[72:73], 0
	v_mov_b64_e32 v[74:75], 0
	v_mov_b64_e32 v[76:77], 0
	v_mov_b64_e32 v[78:79], 0
	v_mov_b64_e32 v[80:81], 0
	v_mov_b64_e32 v[82:83], 0
	v_mov_b64_e32 v[84:85], 0
	v_mov_b64_e32 v[86:87], 0
	v_mov_b64_e32 v[88:89], 0
	v_mov_b64_e32 v[90:91], 0
	v_mov_b64_e32 v[92:93], 0
	v_mov_b64_e32 v[94:95], 0
	v_mov_b64_e32 v[96:97], 0
	v_mov_b64_e32 v[98:99], 0
	v_mov_b64_e32 v[100:101], 0
	v_mov_b64_e32 v[102:103], 0
	v_mov_b64_e32 v[104:105], 0
	v_mov_b64_e32 v[106:107], 0
	v_mov_b64_e32 v[108:109], 0
	v_mov_b64_e32 v[110:111], 0
	v_mov_b64_e32 v[112:113], 0
	v_mov_b64_e32 v[114:115], 0
	v_mov_b64_e32 v[116:117], 0
	v_mov_b64_e32 v[118:119], 0
	v_mov_b64_e32 v[120:121], 0
	v_mov_b64_e32 v[122:123], 0
	v_mov_b64_e32 v[124:125], 0
	v_mov_b64_e32 v[126:127], 0

.LBB0_862:
	s_add_u32 s26, s26, 0x80080
	s_addc_u32 s27, s27, 0
	s_add_u32 s17, s28, 0x100
	v_mov_b32_e32 v0, 0
	s_addc_u32 s19, s29, 0
	s_mov_b32 s21, -2
	v_mov_b64_e32 v[0:1], 0
	v_mov_b64_e32 v[2:3], 0
	v_mov_b64_e32 v[4:5], 0
	v_mov_b64_e32 v[6:7], 0
	v_mov_b64_e32 v[8:9], 0
	v_mov_b64_e32 v[10:11], 0
	v_mov_b64_e32 v[12:13], 0
	v_mov_b64_e32 v[14:15], 0
	v_mov_b64_e32 v[16:17], 0
	v_mov_b64_e32 v[18:19], 0
	v_mov_b64_e32 v[20:21], 0
	v_mov_b64_e32 v[22:23], 0
	v_mov_b64_e32 v[24:25], 0
	v_mov_b64_e32 v[26:27], 0
	v_mov_b64_e32 v[28:29], 0
	v_mov_b64_e32 v[30:31], 0
	v_mov_b64_e32 v[32:33], 0
	v_mov_b64_e32 v[34:35], 0
	v_mov_b64_e32 v[36:37], 0
	v_mov_b64_e32 v[38:39], 0
	v_mov_b64_e32 v[40:41], 0
	v_mov_b64_e32 v[42:43], 0
	v_mov_b64_e32 v[44:45], 0
	v_mov_b64_e32 v[46:47], 0
	v_mov_b64_e32 v[48:49], 0
	v_mov_b64_e32 v[50:51], 0
	v_mov_b64_e32 v[52:53], 0
	v_mov_b64_e32 v[54:55], 0
	v_mov_b64_e32 v[56:57], 0
	v_mov_b64_e32 v[58:59], 0
	v_mov_b64_e32 v[60:61], 0
	v_mov_b64_e32 v[62:63], 0
	v_mov_b64_e32 v[64:65], 0
	v_mov_b64_e32 v[66:67], 0
	v_mov_b64_e32 v[68:69], 0
	v_mov_b64_e32 v[70:71], 0
	v_mov_b64_e32 v[72:73], 0
	v_mov_b64_e32 v[74:75], 0
	v_mov_b64_e32 v[76:77], 0
	v_mov_b64_e32 v[78:79], 0
	v_mov_b64_e32 v[80:81], 0
	v_mov_b64_e32 v[82:83], 0
	v_mov_b64_e32 v[84:85], 0
	v_mov_b64_e32 v[86:87], 0
	v_mov_b64_e32 v[88:89], 0
	v_mov_b64_e32 v[90:91], 0
	v_mov_b64_e32 v[92:93], 0
	v_mov_b64_e32 v[94:95], 0
	v_mov_b64_e32 v[96:97], 0
	v_mov_b64_e32 v[98:99], 0
	v_mov_b64_e32 v[100:101], 0
	v_mov_b64_e32 v[102:103], 0
	v_mov_b64_e32 v[104:105], 0
	v_mov_b64_e32 v[106:107], 0
	v_mov_b64_e32 v[108:109], 0
	v_mov_b64_e32 v[110:111], 0
	v_mov_b64_e32 v[112:113], 0
	v_mov_b64_e32 v[114:115], 0
	v_mov_b64_e32 v[116:117], 0
	v_mov_b64_e32 v[118:119], 0
	v_mov_b64_e32 v[120:121], 0
	v_mov_b64_e32 v[122:123], 0
	v_mov_b64_e32 v[124:125], 0
	v_mov_b64_e32 v[126:127], 0

.LBB0_984:
	s_ashr_i32 s59, s58, 31
	s_lshl_b64 s[60:61], s[58:59], 20
	s_add_u32 s60, s72, s60
	s_addc_u32 s61, s73, s61
	s_and_b64 s[62:63], s[18:19], exec
	s_cselect_b32 s21, s61, s23
	s_cselect_b32 s59, s60, s22
	s_ashr_i32 s57, s56, 31
	s_lshl_b64 s[62:63], s[56:57], 20
	s_add_u32 s62, s74, s62
	s_addc_u32 s63, s75, s63
	s_and_b64 s[66:67], s[18:19], exec
	s_cselect_b32 s57, s63, s65
	s_cselect_b32 s70, s62, s64
	s_add_u32 s22, s22, 0x80080
	s_addc_u32 s23, s23, 0
	s_add_u32 s71, s64, 0x100
	v_mov_b32_e32 v0, 0
	s_addc_u32 s95, s65, 0
	s_mov_b32 s96, -2
	v_mov_b64_e32 v[0:1], 0
	v_mov_b64_e32 v[2:3], 0
	v_mov_b64_e32 v[4:5], 0
	v_mov_b64_e32 v[6:7], 0
	v_mov_b64_e32 v[8:9], 0
	v_mov_b64_e32 v[10:11], 0
	v_mov_b64_e32 v[12:13], 0
	v_mov_b64_e32 v[14:15], 0
	v_mov_b64_e32 v[16:17], 0
	v_mov_b64_e32 v[18:19], 0
	v_mov_b64_e32 v[20:21], 0
	v_mov_b64_e32 v[22:23], 0
	v_mov_b64_e32 v[24:25], 0
	v_mov_b64_e32 v[26:27], 0
	v_mov_b64_e32 v[28:29], 0
	v_mov_b64_e32 v[30:31], 0
	v_mov_b64_e32 v[32:33], 0
	v_mov_b64_e32 v[34:35], 0
	v_mov_b64_e32 v[36:37], 0
	v_mov_b64_e32 v[38:39], 0
	v_mov_b64_e32 v[40:41], 0
	v_mov_b64_e32 v[42:43], 0
	v_mov_b64_e32 v[44:45], 0
	v_mov_b64_e32 v[46:47], 0
	v_mov_b64_e32 v[48:49], 0
	v_mov_b64_e32 v[50:51], 0
	v_mov_b64_e32 v[52:53], 0
	v_mov_b64_e32 v[54:55], 0
	v_mov_b64_e32 v[56:57], 0
	v_mov_b64_e32 v[58:59], 0
	v_mov_b64_e32 v[60:61], 0
	v_mov_b64_e32 v[62:63], 0
	v_mov_b64_e32 v[64:65], 0
	v_mov_b64_e32 v[66:67], 0
	v_mov_b64_e32 v[68:69], 0
	v_mov_b64_e32 v[70:71], 0
	v_mov_b64_e32 v[72:73], 0
	v_mov_b64_e32 v[74:75], 0
	v_mov_b64_e32 v[76:77], 0
	v_mov_b64_e32 v[78:79], 0
	v_mov_b64_e32 v[80:81], 0
	v_mov_b64_e32 v[82:83], 0
	v_mov_b64_e32 v[84:85], 0
	v_mov_b64_e32 v[86:87], 0
	v_mov_b64_e32 v[88:89], 0
	v_mov_b64_e32 v[90:91], 0
	v_mov_b64_e32 v[92:93], 0
	v_mov_b64_e32 v[94:95], 0
	v_mov_b64_e32 v[96:97], 0
	v_mov_b64_e32 v[98:99], 0
	v_mov_b64_e32 v[100:101], 0
	v_mov_b64_e32 v[102:103], 0
	v_mov_b64_e32 v[104:105], 0
	v_mov_b64_e32 v[106:107], 0
	v_mov_b64_e32 v[108:109], 0
	v_mov_b64_e32 v[110:111], 0
	v_mov_b64_e32 v[112:113], 0
	v_mov_b64_e32 v[114:115], 0
	v_mov_b64_e32 v[116:117], 0
	v_mov_b64_e32 v[118:119], 0
	v_mov_b64_e32 v[120:121], 0
	v_mov_b64_e32 v[122:123], 0
	v_mov_b64_e32 v[124:125], 0
	v_mov_b64_e32 v[126:127], 0

.LBB0_1148:
	s_add_u32 s56, s28, 0x100
	v_mov_b32_e32 v0, 0
	s_addc_u32 s57, s29, 0
	s_mov_b32 s58, -2
	v_mov_b64_e32 v[0:1], 0
	v_mov_b64_e32 v[2:3], 0
	v_mov_b64_e32 v[4:5], 0
	v_mov_b64_e32 v[6:7], 0
	v_mov_b64_e32 v[8:9], 0
	v_mov_b64_e32 v[10:11], 0
	v_mov_b64_e32 v[12:13], 0
	v_mov_b64_e32 v[14:15], 0
	v_mov_b64_e32 v[16:17], 0
	v_mov_b64_e32 v[18:19], 0
	v_mov_b64_e32 v[20:21], 0
	v_mov_b64_e32 v[22:23], 0
	v_mov_b64_e32 v[24:25], 0
	v_mov_b64_e32 v[26:27], 0
	v_mov_b64_e32 v[28:29], 0
	v_mov_b64_e32 v[30:31], 0
	v_mov_b64_e32 v[32:33], 0
	v_mov_b64_e32 v[34:35], 0
	v_mov_b64_e32 v[36:37], 0
	v_mov_b64_e32 v[38:39], 0
	v_mov_b64_e32 v[40:41], 0
	v_mov_b64_e32 v[42:43], 0
	v_mov_b64_e32 v[44:45], 0
	v_mov_b64_e32 v[46:47], 0
	v_mov_b64_e32 v[48:49], 0
	v_mov_b64_e32 v[50:51], 0
	v_mov_b64_e32 v[52:53], 0
	v_mov_b64_e32 v[54:55], 0
	v_mov_b64_e32 v[56:57], 0
	v_mov_b64_e32 v[58:59], 0
	v_mov_b64_e32 v[60:61], 0
	v_mov_b64_e32 v[62:63], 0
	v_mov_b64_e32 v[64:65], 0
	v_mov_b64_e32 v[66:67], 0
	v_mov_b64_e32 v[68:69], 0
	v_mov_b64_e32 v[70:71], 0
	v_mov_b64_e32 v[72:73], 0
	v_mov_b64_e32 v[74:75], 0
	v_mov_b64_e32 v[76:77], 0
	v_mov_b64_e32 v[78:79], 0
	v_mov_b64_e32 v[80:81], 0
	v_mov_b64_e32 v[82:83], 0
	v_mov_b64_e32 v[84:85], 0
	v_mov_b64_e32 v[86:87], 0
	v_mov_b64_e32 v[88:89], 0
	v_mov_b64_e32 v[90:91], 0
	v_mov_b64_e32 v[92:93], 0
	v_mov_b64_e32 v[94:95], 0
	v_mov_b64_e32 v[96:97], 0
	v_mov_b64_e32 v[98:99], 0
	v_mov_b64_e32 v[100:101], 0
	v_mov_b64_e32 v[102:103], 0
	v_mov_b64_e32 v[104:105], 0
	v_mov_b64_e32 v[106:107], 0
	v_mov_b64_e32 v[108:109], 0
	v_mov_b64_e32 v[110:111], 0
	v_mov_b64_e32 v[112:113], 0
	v_mov_b64_e32 v[114:115], 0
	v_mov_b64_e32 v[116:117], 0
	v_mov_b64_e32 v[118:119], 0
	v_mov_b64_e32 v[120:121], 0
	v_mov_b64_e32 v[122:123], 0
	v_mov_b64_e32 v[124:125], 0
	v_mov_b64_e32 v[126:127], 0

.LBB0_1169:
	s_add_u32 s54, s24, 0x100
	v_mov_b32_e32 v0, 0
	s_addc_u32 s55, s25, 0
	s_mov_b32 s56, -2
	v_mov_b64_e32 v[0:1], 0
	v_mov_b64_e32 v[2:3], 0
	v_mov_b64_e32 v[4:5], 0
	v_mov_b64_e32 v[6:7], 0
	v_mov_b64_e32 v[8:9], 0
	v_mov_b64_e32 v[10:11], 0
	v_mov_b64_e32 v[12:13], 0
	v_mov_b64_e32 v[14:15], 0
	v_mov_b64_e32 v[16:17], 0
	v_mov_b64_e32 v[18:19], 0
	v_mov_b64_e32 v[20:21], 0
	v_mov_b64_e32 v[22:23], 0
	v_mov_b64_e32 v[24:25], 0
	v_mov_b64_e32 v[26:27], 0
	v_mov_b64_e32 v[28:29], 0
	v_mov_b64_e32 v[30:31], 0
	v_mov_b64_e32 v[32:33], 0
	v_mov_b64_e32 v[34:35], 0
	v_mov_b64_e32 v[36:37], 0
	v_mov_b64_e32 v[38:39], 0
	v_mov_b64_e32 v[40:41], 0
	v_mov_b64_e32 v[42:43], 0
	v_mov_b64_e32 v[44:45], 0
	v_mov_b64_e32 v[46:47], 0
	v_mov_b64_e32 v[48:49], 0
	v_mov_b64_e32 v[50:51], 0
	v_mov_b64_e32 v[52:53], 0
	v_mov_b64_e32 v[54:55], 0
	v_mov_b64_e32 v[56:57], 0
	v_mov_b64_e32 v[58:59], 0
	v_mov_b64_e32 v[60:61], 0
	v_mov_b64_e32 v[62:63], 0
	v_mov_b64_e32 v[64:65], 0
	v_mov_b64_e32 v[66:67], 0
	v_mov_b64_e32 v[68:69], 0
	v_mov_b64_e32 v[70:71], 0
	v_mov_b64_e32 v[72:73], 0
	v_mov_b64_e32 v[74:75], 0
	v_mov_b64_e32 v[76:77], 0
	v_mov_b64_e32 v[78:79], 0
	v_mov_b64_e32 v[80:81], 0
	v_mov_b64_e32 v[82:83], 0
	v_mov_b64_e32 v[84:85], 0
	v_mov_b64_e32 v[86:87], 0
	v_mov_b64_e32 v[88:89], 0
	v_mov_b64_e32 v[90:91], 0
	v_mov_b64_e32 v[92:93], 0
	v_mov_b64_e32 v[94:95], 0
	v_mov_b64_e32 v[96:97], 0
	v_mov_b64_e32 v[98:99], 0
	v_mov_b64_e32 v[100:101], 0
	v_mov_b64_e32 v[102:103], 0
	v_mov_b64_e32 v[104:105], 0
	v_mov_b64_e32 v[106:107], 0
	v_mov_b64_e32 v[108:109], 0
	v_mov_b64_e32 v[110:111], 0
	v_mov_b64_e32 v[112:113], 0
	v_mov_b64_e32 v[114:115], 0
	v_mov_b64_e32 v[116:117], 0
	v_mov_b64_e32 v[118:119], 0
	v_mov_b64_e32 v[120:121], 0
	v_mov_b64_e32 v[122:123], 0
	v_mov_b64_e32 v[124:125], 0
	v_mov_b64_e32 v[126:127], 0
